# strategy 7 cont: NA score-scale v_pk_fma_f32/v_pk_mul_f32 (beside QK MFMAs) also split into scalar ops
# baseline (speedup 1.0000x reference)
; #define LAS __attribute__((address_space(3)))
; __device__ void na_item(KParams p, int l, int item, LAS unsigned char* lds) {
;     ...
;                     if (lat_st) {
;                         const LAS float* rpr = RPB + min(max(rk - rq[t] + 7, 0), 14) * 31;
;                         const unsigned vm = act[t] ? vmask : 0u;
; #pragma unroll
;                         for (int i = 0; i < 8; ++i) s2[i] = rpr[dcolv[i]];
; #pragma unroll
;                         for (int i = 0; i < 8; ++i) s2[i] = (vm >> i) & 1 ? sa[i >> 2][i & 3] * sc2 + s2[i] : -INFINITY;
;                     } else {
; #pragma unroll
;                         for (int i = 0; i < 8; ++i) s2[i] = sa[i >> 2][i & 3] * sc2;
;                     }
.LBB0_217:
	s_or_b64 exec, exec, s[28:29]
	s_waitcnt lgkmcnt(4)
	v_fma_f32 v154, v148, s22, v170
	v_fma_f32 v155, v149, s22, v171
	v_fmac_f32_e32 v235, 0x3e0293ee, v147
	v_cndmask_b32_e64 v171, v155, v220, s[46:47]
	v_cndmask_b32_e64 v170, v154, v220, s[48:49]
	s_waitcnt lgkmcnt(2)
	v_fma_f32 v154, v150, s22, v172
	v_fma_f32 v155, v151, s22, v173
	v_cndmask_b32_e64 v235, v235, v220, s[44:45]
	v_cndmask_b32_e64 v173, v155, v220, s[50:51]
	v_cndmask_b32_e64 v172, v154, v220, s[52:53]
	s_waitcnt lgkmcnt(0)
	v_fma_f32 v154, v152, s22, v174
	v_fma_f32 v155, v153, s22, v175
	s_mov_b64 s[28:29], 0
	v_cndmask_b32_e64 v175, v155, v220, s[54:55]
	v_cndmask_b32_e64 v174, v154, v220, s[56:57]
.LBB0_218:
	s_and_b64 vcc, exec, s[28:29]
	s_cbranch_vccz .LBB0_220
	s_nop 2
	v_mul_f32_e32 v234, 0x3e0293ee, v146
	v_mul_f32_e32 v235, 0x3e0293ee, v147
	v_mul_f32_e32 v170, s22, v148
	v_mul_f32_e32 v171, s22, v149
	v_mul_f32_e32 v172, s22, v150
	v_mul_f32_e32 v173, s22, v151
	v_mul_f32_e32 v174, s22, v152
	v_mul_f32_e32 v175, s22, v153

; #define LAS __attribute__((address_space(3)))
; __device__ void na_item(KParams p, int l, int item, LAS unsigned char* lds) {
;     ...
;                     if (lat_st) {
;                         const LAS float* rpr = RPB + min(max(rk - rq[t] + 7, 0), 14) * 31;
;                         const unsigned vm = act[t] ? vmask : 0u;
; #pragma unroll
;                         for (int i = 0; i < 8; ++i) s2[i] = rpr[dcolv[i]];
; #pragma unroll
;                         for (int i = 0; i < 8; ++i) s2[i] = (vm >> i) & 1 ? sa[i >> 2][i & 3] * sc2 + s2[i] : -INFINITY;
;                     } else {
; #pragma unroll
;                         for (int i = 0; i < 8; ++i) s2[i] = sa[i >> 2][i & 3] * sc2;
;                     }
.LBB0_223:
	s_or_b64 exec, exec, s[28:29]
	s_waitcnt lgkmcnt(6)
	v_fmac_f32_e32 v128, 0x3e0293ee, v131
	s_waitcnt lgkmcnt(4)
	v_fma_f32 v126, v132, s22, v126
	v_fma_f32 v127, v133, s22, v127
	s_waitcnt lgkmcnt(2)
	v_fma_f32 v124, v118, s22, v124
	v_fma_f32 v125, v119, s22, v125
	s_waitcnt lgkmcnt(0)
	v_fma_f32 v122, v120, s22, v122
	v_fma_f32 v123, v121, s22, v123
	v_cndmask_b32_e64 v149, v128, v220, s[60:61]
	v_cndmask_b32_e64 v137, v127, v220, s[62:63]
	v_cndmask_b32_e64 v136, v126, v220, s[64:65]
	v_cndmask_b32_e64 v129, v125, v220, s[66:67]
	v_cndmask_b32_e64 v128, v124, v220, s[68:69]
	v_cndmask_b32_e64 v135, v123, v220, s[70:71]
	v_cndmask_b32_e64 v134, v122, v220, s[72:73]
	s_mov_b64 s[28:29], 0
.LBB0_224:
	s_and_b64 vcc, exec, s[28:29]
	s_cbranch_vccz .LBB0_226
	v_mul_f32_e32 v144, 0x3e0293ee, v130
	v_mul_f32_e32 v149, 0x3e0293ee, v131
	v_mul_f32_e32 v136, s22, v132
	v_mul_f32_e32 v137, s22, v133
	s_nop 0
	v_mul_f32_e32 v128, s22, v118
	v_mul_f32_e32 v129, s22, v119
	v_mul_f32_e32 v134, s22, v120
	v_mul_f32_e32 v135, s22, v121
